# v122 stack plus relaxed first-trip waits (in-proj x2, ffn-up) and no per-segment s_setprio toggles in the GEMM K-loops
# baseline (speedup 1.0000x reference)
.Lrwd_fu0:
	s_waitcnt lgkmcnt(0)
	s_barrier
	s_waitcnt lgkmcnt(0)
	v_mfma_f32_16x16x32_bf16 v[124:127], v[144:147], v[178:181], v[124:127]
	v_mfma_f32_16x16x32_bf16 v[116:119], v[152:155], v[178:181], v[116:119]
	v_mfma_f32_16x16x32_bf16 v[108:111], v[144:147], v[186:189], v[108:111]
	v_mfma_f32_16x16x32_bf16 v[100:103], v[152:155], v[186:189], v[100:103]
	v_mfma_f32_16x16x32_bf16 v[92:95], v[144:147], v[212:215], v[92:95]
	v_mfma_f32_16x16x32_bf16 v[84:87], v[152:155], v[212:215], v[84:87]
	v_mfma_f32_16x16x32_bf16 v[76:79], v[144:147], v[220:223], v[76:79]
	v_mfma_f32_16x16x32_bf16 v[68:71], v[152:155], v[220:223], v[68:71]
	v_mfma_f32_16x16x32_bf16 v[124:127], v[148:151], v[182:185], v[124:127]
	v_mfma_f32_16x16x32_bf16 v[116:119], v[156:159], v[182:185], v[116:119]
	v_mfma_f32_16x16x32_bf16 v[108:111], v[148:151], v[208:211], v[108:111]
	v_mfma_f32_16x16x32_bf16 v[100:103], v[156:159], v[208:211], v[100:103]
	v_mfma_f32_16x16x32_bf16 v[92:95], v[148:151], v[216:219], v[92:95]
	v_mfma_f32_16x16x32_bf16 v[84:87], v[156:159], v[216:219], v[84:87]
	v_mfma_f32_16x16x32_bf16 v[76:79], v[148:151], v[224:227], v[76:79]
	v_mfma_f32_16x16x32_bf16 v[68:71], v[156:159], v[224:227], v[68:71]
	v_mfma_f32_16x16x32_bf16 v[120:123], v[160:163], v[178:181], v[120:123]
	v_mfma_f32_16x16x32_bf16 v[112:115], v[168:171], v[178:181], v[112:115]
	v_mfma_f32_16x16x32_bf16 v[104:107], v[160:163], v[186:189], v[104:107]
	v_mfma_f32_16x16x32_bf16 v[96:99], v[168:171], v[186:189], v[96:99]
	v_mfma_f32_16x16x32_bf16 v[88:91], v[160:163], v[212:215], v[88:91]
	v_mfma_f32_16x16x32_bf16 v[80:83], v[168:171], v[212:215], v[80:83]
	v_mfma_f32_16x16x32_bf16 v[72:75], v[160:163], v[220:223], v[72:75]
	v_mfma_f32_16x16x32_bf16 v[64:67], v[168:171], v[220:223], v[64:67]
	v_mfma_f32_16x16x32_bf16 v[120:123], v[164:167], v[182:185], v[120:123]
	v_mfma_f32_16x16x32_bf16 v[112:115], v[172:175], v[182:185], v[112:115]
	v_mfma_f32_16x16x32_bf16 v[104:107], v[164:167], v[208:211], v[104:107]
	v_mfma_f32_16x16x32_bf16 v[96:99], v[172:175], v[208:211], v[96:99]
	v_mfma_f32_16x16x32_bf16 v[88:91], v[164:167], v[216:219], v[88:91]
	v_mfma_f32_16x16x32_bf16 v[80:83], v[172:175], v[216:219], v[80:83]
	v_mfma_f32_16x16x32_bf16 v[72:75], v[164:167], v[224:227], v[72:75]
	v_mfma_f32_16x16x32_bf16 v[64:67], v[172:175], v[224:227], v[64:67]
	s_barrier
	s_add_i32 s0, s22, s35
	v_lshl_add_u64 v[228:229], s[58:59], 0, v[132:133]
	s_mov_b32 m0, s0
	ds_read_b128 v[178:181], v143 offset:16384
	ds_read_b128 v[182:185], v143 offset:17408
	ds_read_b128 v[186:189], v143 offset:18432
	ds_read_b128 v[208:211], v143 offset:19456
	ds_read_b128 v[212:215], v143 offset:20480
	ds_read_b128 v[216:219], v143 offset:21504
	ds_read_b128 v[220:223], v143 offset:22528
	ds_read_b128 v[224:227], v143 offset:23552
	global_load_lds_dwordx4 v[228:229], off
	s_add_i32 m0, s0, 0x2000
	s_add_u32 s0, s58, 0x10000
	v_lshl_add_u64 v[230:231], s[58:59], 0, v[128:129]
	s_addc_u32 s1, s59, 0
	s_add_i32 s22, s37, s35
	global_load_lds_dwordx4 v[230:231], off
	v_lshl_add_u64 v[232:233], s[0:1], 0, v[132:133]
	s_mov_b32 m0, s22
	v_lshl_add_u64 v[234:235], s[60:61], 0, v[130:131]
	global_load_lds_dwordx4 v[232:233], off
	v_lshl_add_u64 v[232:233], s[0:1], 0, v[128:129]
	s_add_i32 m0, s22, 0x2000
	s_nop 0
	global_load_lds_dwordx4 v[232:233], off
	v_lshl_add_u64 v[232:233], s[60:61], 0, v[134:135]
	s_mov_b32 m0, s66
	s_nop 0
	global_load_lds_dwordx4 v[232:233], off
	s_mov_b32 m0, s67
	s_nop 0
	global_load_lds_dwordx4 v[234:235], off
	s_cmp_eq_u32 s64, -2
	s_cbranch_scc0 .Lrw8_fu1
	s_cmp_gt_u32 s50, 1
	s_cbranch_scc0 .Lrw8_fu1
	s_waitcnt vmcnt(16)
	s_branch .Lrwd_fu1

.Lrwd_fu1:
	s_waitcnt lgkmcnt(0)
	s_barrier
	s_waitcnt lgkmcnt(0)
	v_mfma_f32_16x16x32_bf16 v[60:63], v[144:147], v[178:181], v[60:63]
	v_mfma_f32_16x16x32_bf16 v[52:55], v[152:155], v[178:181], v[52:55]
	v_mfma_f32_16x16x32_bf16 v[44:47], v[144:147], v[186:189], v[44:47]
	v_mfma_f32_16x16x32_bf16 v[36:39], v[152:155], v[186:189], v[36:39]
	v_mfma_f32_16x16x32_bf16 v[28:31], v[144:147], v[212:215], v[28:31]
	v_mfma_f32_16x16x32_bf16 v[20:23], v[152:155], v[212:215], v[20:23]
	v_mfma_f32_16x16x32_bf16 v[12:15], v[144:147], v[220:223], v[12:15]
	v_mfma_f32_16x16x32_bf16 v[4:7], v[152:155], v[220:223], v[4:7]
	v_mfma_f32_16x16x32_bf16 v[60:63], v[148:151], v[182:185], v[60:63]
	v_mfma_f32_16x16x32_bf16 v[52:55], v[156:159], v[182:185], v[52:55]
	v_mfma_f32_16x16x32_bf16 v[44:47], v[148:151], v[208:211], v[44:47]
	v_mfma_f32_16x16x32_bf16 v[36:39], v[156:159], v[208:211], v[36:39]
	v_mfma_f32_16x16x32_bf16 v[28:31], v[148:151], v[216:219], v[28:31]
	v_mfma_f32_16x16x32_bf16 v[20:23], v[156:159], v[216:219], v[20:23]
	v_mfma_f32_16x16x32_bf16 v[12:15], v[148:151], v[224:227], v[12:15]
	v_mfma_f32_16x16x32_bf16 v[4:7], v[156:159], v[224:227], v[4:7]
	v_mfma_f32_16x16x32_bf16 v[56:59], v[160:163], v[178:181], v[56:59]
	v_mfma_f32_16x16x32_bf16 v[48:51], v[168:171], v[178:181], v[48:51]
	v_mfma_f32_16x16x32_bf16 v[40:43], v[160:163], v[186:189], v[40:43]
	v_mfma_f32_16x16x32_bf16 v[32:35], v[168:171], v[186:189], v[32:35]
	v_mfma_f32_16x16x32_bf16 v[24:27], v[160:163], v[212:215], v[24:27]
	v_mfma_f32_16x16x32_bf16 v[16:19], v[168:171], v[212:215], v[16:19]
	v_mfma_f32_16x16x32_bf16 v[8:11], v[160:163], v[220:223], v[8:11]
	v_mfma_f32_16x16x32_bf16 v[0:3], v[168:171], v[220:223], v[0:3]
	v_mfma_f32_16x16x32_bf16 v[56:59], v[164:167], v[182:185], v[56:59]
	v_mfma_f32_16x16x32_bf16 v[48:51], v[172:175], v[182:185], v[48:51]
	v_mfma_f32_16x16x32_bf16 v[40:43], v[164:167], v[208:211], v[40:43]
	v_mfma_f32_16x16x32_bf16 v[32:35], v[172:175], v[208:211], v[32:35]
	v_mfma_f32_16x16x32_bf16 v[24:27], v[164:167], v[216:219], v[24:27]
	v_mfma_f32_16x16x32_bf16 v[16:19], v[172:175], v[216:219], v[16:19]
	v_mfma_f32_16x16x32_bf16 v[8:11], v[164:167], v[224:227], v[8:11]
	v_mfma_f32_16x16x32_bf16 v[0:3], v[172:175], v[224:227], v[0:3]
	s_barrier
	s_add_i32 s22, 0, 0x18000
	s_add_i32 s37, 0, 0x1c000
	v_add_u32_e32 v156, s22, v142
	v_add_u32_e32 v172, s37, v142
	ds_read_b128 v[144:147], v156
	ds_read_b128 v[148:151], v156 offset:1024
	ds_read_b128 v[152:155], v156 offset:2048
	ds_read_b128 v[156:159], v156 offset:3072
	ds_read_b128 v[160:163], v172
	ds_read_b128 v[164:167], v172 offset:1024
	ds_read_b128 v[168:171], v172 offset:2048
	ds_read_b128 v[172:175], v172 offset:3072
	s_add_u32 s0, s60, 0x40000
	s_addc_u32 s1, s61, 0
	s_mov_b32 m0, s68
	v_lshl_add_u64 v[236:237], s[0:1], 0, v[134:135]
	ds_read_b128 v[178:181], v143 offset:32768
	ds_read_b128 v[182:185], v143 offset:33792
	ds_read_b128 v[186:189], v143 offset:34816
	ds_read_b128 v[208:211], v143 offset:35840
	ds_read_b128 v[212:215], v143 offset:36864
	ds_read_b128 v[216:219], v143 offset:37888
	ds_read_b128 v[220:223], v143 offset:38912
	ds_read_b128 v[224:227], v143 offset:39936
	global_load_lds_dwordx4 v[236:237], off
	v_lshl_add_u64 v[236:237], s[0:1], 0, v[130:131]
	s_mov_b32 m0, s69
	s_nop 0
	global_load_lds_dwordx4 v[236:237], off
	s_cmp_eq_u32 s64, -2
	s_cbranch_scc0 .Lrw8_fu2
	s_cmp_gt_u32 s50, 1
	s_cbranch_scc0 .Lrw8_fu2
	s_waitcnt vmcnt(18)
	s_branch .Lrwd_fu2

.Lrwd_fu2:
	s_waitcnt lgkmcnt(0)
	s_barrier
	s_waitcnt lgkmcnt(0)
	v_mfma_f32_16x16x32_bf16 v[124:127], v[144:147], v[178:181], v[124:127]
	v_mfma_f32_16x16x32_bf16 v[116:119], v[152:155], v[178:181], v[116:119]
	v_mfma_f32_16x16x32_bf16 v[108:111], v[144:147], v[186:189], v[108:111]
	v_mfma_f32_16x16x32_bf16 v[100:103], v[152:155], v[186:189], v[100:103]
	v_mfma_f32_16x16x32_bf16 v[92:95], v[144:147], v[212:215], v[92:95]
	v_mfma_f32_16x16x32_bf16 v[84:87], v[152:155], v[212:215], v[84:87]
	v_mfma_f32_16x16x32_bf16 v[76:79], v[144:147], v[220:223], v[76:79]
	v_mfma_f32_16x16x32_bf16 v[68:71], v[152:155], v[220:223], v[68:71]
	v_mfma_f32_16x16x32_bf16 v[124:127], v[148:151], v[182:185], v[124:127]
	v_mfma_f32_16x16x32_bf16 v[116:119], v[156:159], v[182:185], v[116:119]
	v_mfma_f32_16x16x32_bf16 v[108:111], v[148:151], v[208:211], v[108:111]
	v_mfma_f32_16x16x32_bf16 v[100:103], v[156:159], v[208:211], v[100:103]
	v_mfma_f32_16x16x32_bf16 v[92:95], v[148:151], v[216:219], v[92:95]
	v_mfma_f32_16x16x32_bf16 v[84:87], v[156:159], v[216:219], v[84:87]
	v_mfma_f32_16x16x32_bf16 v[76:79], v[148:151], v[224:227], v[76:79]
	v_mfma_f32_16x16x32_bf16 v[68:71], v[156:159], v[224:227], v[68:71]
	v_mfma_f32_16x16x32_bf16 v[120:123], v[160:163], v[178:181], v[120:123]
	v_mfma_f32_16x16x32_bf16 v[112:115], v[168:171], v[178:181], v[112:115]
	v_mfma_f32_16x16x32_bf16 v[104:107], v[160:163], v[186:189], v[104:107]
	v_mfma_f32_16x16x32_bf16 v[96:99], v[168:171], v[186:189], v[96:99]
	v_mfma_f32_16x16x32_bf16 v[88:91], v[160:163], v[212:215], v[88:91]
	v_mfma_f32_16x16x32_bf16 v[80:83], v[168:171], v[212:215], v[80:83]
	v_mfma_f32_16x16x32_bf16 v[72:75], v[160:163], v[220:223], v[72:75]
	v_mfma_f32_16x16x32_bf16 v[64:67], v[168:171], v[220:223], v[64:67]
	v_mfma_f32_16x16x32_bf16 v[120:123], v[164:167], v[182:185], v[120:123]
	v_mfma_f32_16x16x32_bf16 v[112:115], v[172:175], v[182:185], v[112:115]
	v_mfma_f32_16x16x32_bf16 v[104:107], v[164:167], v[208:211], v[104:107]
	v_mfma_f32_16x16x32_bf16 v[96:99], v[172:175], v[208:211], v[96:99]
	v_mfma_f32_16x16x32_bf16 v[88:91], v[164:167], v[216:219], v[88:91]
	v_mfma_f32_16x16x32_bf16 v[80:83], v[172:175], v[216:219], v[80:83]
	v_mfma_f32_16x16x32_bf16 v[72:75], v[164:167], v[224:227], v[72:75]
	v_mfma_f32_16x16x32_bf16 v[64:67], v[172:175], v[224:227], v[64:67]
	s_barrier
	s_add_i32 s0, s22, s35
	v_lshl_add_u64 v[228:229], v[228:229], 0, s[26:27]
	s_mov_b32 m0, s0
	ds_read_b128 v[178:181], v143 offset:49152
	ds_read_b128 v[182:185], v143 offset:50176
	ds_read_b128 v[186:189], v143 offset:51200
	ds_read_b128 v[208:211], v143 offset:52224
	ds_read_b128 v[212:215], v143 offset:53248
	ds_read_b128 v[216:219], v143 offset:54272
	ds_read_b128 v[220:223], v143 offset:55296
	ds_read_b128 v[224:227], v143 offset:56320
	global_load_lds_dwordx4 v[228:229], off
	s_add_i32 m0, s0, 0x2000
	s_add_u32 s0, s58, 0x10080
	v_lshl_add_u64 v[228:229], v[230:231], 0, s[26:27]
	s_addc_u32 s1, s59, 0
	s_add_i32 s22, s37, s35
	global_load_lds_dwordx4 v[228:229], off
	v_lshl_add_u64 v[228:229], s[0:1], 0, v[132:133]
	s_mov_b32 m0, s22
	s_nop 0
	global_load_lds_dwordx4 v[228:229], off
	v_lshl_add_u64 v[228:229], s[0:1], 0, v[128:129]
	s_add_i32 m0, s22, 0x2000
	s_nop 0
	global_load_lds_dwordx4 v[228:229], off
	v_lshl_add_u64 v[228:229], v[232:233], 0, s[26:27]
	s_mov_b32 m0, s48
	s_nop 0
	global_load_lds_dwordx4 v[228:229], off
	v_lshl_add_u64 v[228:229], v[234:235], 0, s[26:27]
	s_mov_b32 m0, s49
	s_nop 0
	global_load_lds_dwordx4 v[228:229], off
	s_waitcnt vmcnt(8)
	s_waitcnt lgkmcnt(0)
	s_barrier
	s_waitcnt lgkmcnt(0)
	v_mfma_f32_16x16x32_bf16 v[60:63], v[144:147], v[178:181], v[60:63]
	v_mfma_f32_16x16x32_bf16 v[52:55], v[152:155], v[178:181], v[52:55]
	v_mfma_f32_16x16x32_bf16 v[44:47], v[144:147], v[186:189], v[44:47]
	v_mfma_f32_16x16x32_bf16 v[36:39], v[152:155], v[186:189], v[36:39]
	v_mfma_f32_16x16x32_bf16 v[28:31], v[144:147], v[212:215], v[28:31]
	v_mfma_f32_16x16x32_bf16 v[20:23], v[152:155], v[212:215], v[20:23]
	v_mfma_f32_16x16x32_bf16 v[12:15], v[144:147], v[220:223], v[12:15]
	v_mfma_f32_16x16x32_bf16 v[4:7], v[152:155], v[220:223], v[4:7]
	v_mfma_f32_16x16x32_bf16 v[60:63], v[148:151], v[182:185], v[60:63]
	v_mfma_f32_16x16x32_bf16 v[52:55], v[156:159], v[182:185], v[52:55]
	v_mfma_f32_16x16x32_bf16 v[44:47], v[148:151], v[208:211], v[44:47]
	v_mfma_f32_16x16x32_bf16 v[36:39], v[156:159], v[208:211], v[36:39]
	v_mfma_f32_16x16x32_bf16 v[28:31], v[148:151], v[216:219], v[28:31]
	v_mfma_f32_16x16x32_bf16 v[20:23], v[156:159], v[216:219], v[20:23]
	v_mfma_f32_16x16x32_bf16 v[12:15], v[148:151], v[224:227], v[12:15]
	v_mfma_f32_16x16x32_bf16 v[4:7], v[156:159], v[224:227], v[4:7]
	v_mfma_f32_16x16x32_bf16 v[56:59], v[160:163], v[178:181], v[56:59]
	v_mfma_f32_16x16x32_bf16 v[48:51], v[168:171], v[178:181], v[48:51]
	v_mfma_f32_16x16x32_bf16 v[40:43], v[160:163], v[186:189], v[40:43]
	v_mfma_f32_16x16x32_bf16 v[32:35], v[168:171], v[186:189], v[32:35]
	v_mfma_f32_16x16x32_bf16 v[24:27], v[160:163], v[212:215], v[24:27]
	v_mfma_f32_16x16x32_bf16 v[16:19], v[168:171], v[212:215], v[16:19]
	v_mfma_f32_16x16x32_bf16 v[8:11], v[160:163], v[220:223], v[8:11]
	v_mfma_f32_16x16x32_bf16 v[0:3], v[168:171], v[220:223], v[0:3]
	v_mfma_f32_16x16x32_bf16 v[56:59], v[164:167], v[182:185], v[56:59]
	v_mfma_f32_16x16x32_bf16 v[48:51], v[172:175], v[182:185], v[48:51]
	v_mfma_f32_16x16x32_bf16 v[40:43], v[164:167], v[208:211], v[40:43]
	v_mfma_f32_16x16x32_bf16 v[32:35], v[172:175], v[208:211], v[32:35]
	v_mfma_f32_16x16x32_bf16 v[24:27], v[164:167], v[216:219], v[24:27]
	v_mfma_f32_16x16x32_bf16 v[16:19], v[172:175], v[216:219], v[16:19]
	v_mfma_f32_16x16x32_bf16 v[8:11], v[164:167], v[224:227], v[8:11]
	v_mfma_f32_16x16x32_bf16 v[0:3], v[172:175], v[224:227], v[0:3]
	s_barrier
	s_add_i32 s64, s64, 2
	s_add_u32 s56, s56, 0x100
	s_addc_u32 s57, s57, 0
	s_add_u32 s62, s62, 0x100
	s_addc_u32 s63, s63, 0
	s_cmp_gt_u32 s64, 13
	s_cbranch_scc0 .LBB0_58
	v_readlane_b32 s0, v252, 28
	v_readlane_b32 s1, v252, 29
	s_and_b64 vcc, exec, s[0:1]
	s_cbranch_vccz .LBB0_61
	s_barrier

.Lrwd_ip0:
	s_waitcnt lgkmcnt(0)
	s_barrier
	s_waitcnt lgkmcnt(0)
	v_mfma_f32_16x16x32_bf16 v[124:127], v[146:149], v[212:215], v[124:127]
	v_mfma_f32_16x16x32_bf16 v[120:123], v[154:157], v[212:215], v[120:123]
	v_mfma_f32_16x16x32_bf16 v[116:119], v[146:149], v[220:223], v[116:119]
	v_mfma_f32_16x16x32_bf16 v[112:115], v[154:157], v[220:223], v[112:115]
	v_mfma_f32_16x16x32_bf16 v[100:103], v[146:149], v[228:231], v[100:103]
	v_mfma_f32_16x16x32_bf16 v[96:99], v[154:157], v[228:231], v[96:99]
	v_mfma_f32_16x16x32_bf16 v[84:87], v[146:149], v[236:239], v[84:87]
	v_mfma_f32_16x16x32_bf16 v[80:83], v[154:157], v[236:239], v[80:83]
	v_mfma_f32_16x16x32_bf16 v[124:127], v[150:153], v[216:219], v[124:127]
	v_mfma_f32_16x16x32_bf16 v[120:123], v[170:173], v[216:219], v[120:123]
	v_mfma_f32_16x16x32_bf16 v[116:119], v[150:153], v[224:227], v[116:119]
	v_mfma_f32_16x16x32_bf16 v[112:115], v[170:173], v[224:227], v[112:115]
	v_mfma_f32_16x16x32_bf16 v[100:103], v[150:153], v[232:235], v[100:103]
	v_mfma_f32_16x16x32_bf16 v[96:99], v[170:173], v[232:235], v[96:99]
	v_mfma_f32_16x16x32_bf16 v[84:87], v[150:153], v[240:243], v[84:87]
	v_mfma_f32_16x16x32_bf16 v[80:83], v[170:173], v[240:243], v[80:83]
	v_mfma_f32_16x16x32_bf16 v[108:111], v[178:181], v[212:215], v[108:111]
	v_mfma_f32_16x16x32_bf16 v[104:107], v[186:189], v[212:215], v[104:107]
	v_mfma_f32_16x16x32_bf16 v[92:95], v[178:181], v[220:223], v[92:95]
	v_mfma_f32_16x16x32_bf16 v[88:91], v[186:189], v[220:223], v[88:91]
	v_mfma_f32_16x16x32_bf16 v[76:79], v[178:181], v[228:231], v[76:79]
	v_mfma_f32_16x16x32_bf16 v[72:75], v[186:189], v[228:231], v[72:75]
	v_mfma_f32_16x16x32_bf16 v[68:71], v[178:181], v[236:239], v[68:71]
	v_mfma_f32_16x16x32_bf16 v[64:67], v[186:189], v[236:239], v[64:67]
	v_mfma_f32_16x16x32_bf16 v[108:111], v[182:185], v[216:219], v[108:111]
	v_mfma_f32_16x16x32_bf16 v[104:107], v[208:211], v[216:219], v[104:107]
	v_mfma_f32_16x16x32_bf16 v[92:95], v[182:185], v[224:227], v[92:95]
	v_mfma_f32_16x16x32_bf16 v[88:91], v[208:211], v[224:227], v[88:91]
	v_mfma_f32_16x16x32_bf16 v[76:79], v[182:185], v[232:235], v[76:79]
	v_mfma_f32_16x16x32_bf16 v[72:75], v[208:211], v[232:235], v[72:75]
	v_mfma_f32_16x16x32_bf16 v[68:71], v[182:185], v[240:243], v[68:71]
	v_mfma_f32_16x16x32_bf16 v[64:67], v[208:211], v[240:243], v[64:67]
	s_barrier
	s_add_i32 s39, s65, s52
	v_lshl_add_u64 v[158:159], s[44:45], 0, v[132:133]
	s_mov_b32 m0, s39
	ds_read_b128 v[212:215], v168 offset:16384
	ds_read_b128 v[216:219], v168 offset:17408
	ds_read_b128 v[220:223], v168 offset:18432
	ds_read_b128 v[224:227], v168 offset:19456
	ds_read_b128 v[228:231], v168 offset:20480
	ds_read_b128 v[232:235], v168 offset:21504
	ds_read_b128 v[236:239], v168 offset:22528
	ds_read_b128 v[240:243], v168 offset:23552
	global_load_lds_dwordx4 v[158:159], off
	s_add_i32 m0, s39, 0x2000
	s_add_u32 s66, s44, 0x10000
	v_lshl_add_u64 v[174:175], s[44:45], 0, v[128:129]
	s_addc_u32 s67, s45, 0
	s_add_i32 s37, s37, s52
	global_load_lds_dwordx4 v[174:175], off
	v_lshl_add_u64 v[244:245], s[66:67], 0, v[132:133]
	s_mov_b32 m0, s37
	v_lshl_add_u64 v[246:247], s[62:63], 0, v[130:131]
	global_load_lds_dwordx4 v[244:245], off
	v_lshl_add_u64 v[244:245], s[66:67], 0, v[128:129]
	s_add_i32 m0, s37, 0x2000
	s_nop 0
	global_load_lds_dwordx4 v[244:245], off
	v_lshl_add_u64 v[244:245], s[62:63], 0, v[134:135]
	s_mov_b32 m0, s56
	s_nop 0
	global_load_lds_dwordx4 v[244:245], off
	s_mov_b32 m0, s57
	s_nop 0
	global_load_lds_dwordx4 v[246:247], off
	s_cmp_eq_u32 s64, -2
	s_cbranch_scc0 .Lrw8_ip1
	s_cmp_gt_u32 s35, 1
	s_cbranch_scc0 .Lrw8_ip1
	s_waitcnt vmcnt(24)
	s_branch .Lrwd_ip1

.Lrwd_ip1:
	s_waitcnt lgkmcnt(0)
	s_barrier
	s_waitcnt lgkmcnt(0)
	v_mfma_f32_16x16x32_bf16 v[60:63], v[146:149], v[212:215], v[60:63]
	v_mfma_f32_16x16x32_bf16 v[56:59], v[154:157], v[212:215], v[56:59]
	v_mfma_f32_16x16x32_bf16 v[52:55], v[146:149], v[220:223], v[52:55]
	v_mfma_f32_16x16x32_bf16 v[48:51], v[154:157], v[220:223], v[48:51]
	v_mfma_f32_16x16x32_bf16 v[36:39], v[146:149], v[228:231], v[36:39]
	v_mfma_f32_16x16x32_bf16 v[32:35], v[154:157], v[228:231], v[32:35]
	v_mfma_f32_16x16x32_bf16 v[20:23], v[146:149], v[236:239], v[20:23]
	v_mfma_f32_16x16x32_bf16 v[16:19], v[154:157], v[236:239], v[16:19]
	v_mfma_f32_16x16x32_bf16 v[60:63], v[150:153], v[216:219], v[60:63]
	v_mfma_f32_16x16x32_bf16 v[56:59], v[170:173], v[216:219], v[56:59]
	v_mfma_f32_16x16x32_bf16 v[52:55], v[150:153], v[224:227], v[52:55]
	v_mfma_f32_16x16x32_bf16 v[48:51], v[170:173], v[224:227], v[48:51]
	v_mfma_f32_16x16x32_bf16 v[36:39], v[150:153], v[232:235], v[36:39]
	v_mfma_f32_16x16x32_bf16 v[32:35], v[170:173], v[232:235], v[32:35]
	v_mfma_f32_16x16x32_bf16 v[20:23], v[150:153], v[240:243], v[20:23]
	v_mfma_f32_16x16x32_bf16 v[16:19], v[170:173], v[240:243], v[16:19]
	v_mfma_f32_16x16x32_bf16 v[44:47], v[178:181], v[212:215], v[44:47]
	v_mfma_f32_16x16x32_bf16 v[40:43], v[186:189], v[212:215], v[40:43]
	v_mfma_f32_16x16x32_bf16 v[28:31], v[178:181], v[220:223], v[28:31]
	v_mfma_f32_16x16x32_bf16 v[24:27], v[186:189], v[220:223], v[24:27]
	v_mfma_f32_16x16x32_bf16 v[12:15], v[178:181], v[228:231], v[12:15]
	v_mfma_f32_16x16x32_bf16 v[8:11], v[186:189], v[228:231], v[8:11]
	v_mfma_f32_16x16x32_bf16 v[4:7], v[178:181], v[236:239], v[4:7]
	v_mfma_f32_16x16x32_bf16 v[0:3], v[186:189], v[236:239], v[0:3]
	v_mfma_f32_16x16x32_bf16 v[44:47], v[182:185], v[216:219], v[44:47]
	v_mfma_f32_16x16x32_bf16 v[40:43], v[208:211], v[216:219], v[40:43]
	v_mfma_f32_16x16x32_bf16 v[28:31], v[182:185], v[224:227], v[28:31]
	v_mfma_f32_16x16x32_bf16 v[24:27], v[208:211], v[224:227], v[24:27]
	v_mfma_f32_16x16x32_bf16 v[12:15], v[182:185], v[232:235], v[12:15]
	v_mfma_f32_16x16x32_bf16 v[8:11], v[208:211], v[232:235], v[8:11]
	v_mfma_f32_16x16x32_bf16 v[4:7], v[182:185], v[240:243], v[4:7]
	v_mfma_f32_16x16x32_bf16 v[0:3], v[208:211], v[240:243], v[0:3]
	s_barrier
	s_add_i32 s37, 0, 0x18000
	v_add_u32_e32 v145, s37, v162
	s_add_i32 s39, 0, 0x1c000
	ds_read_b128 v[146:149], v145
	ds_read_b128 v[150:153], v145 offset:1024
	ds_read_b128 v[154:157], v145 offset:2048
	ds_read_b128 v[170:173], v145 offset:3072
	v_add_u32_e32 v145, s39, v162
	ds_read_b128 v[178:181], v145
	ds_read_b128 v[182:185], v145 offset:1024
	ds_read_b128 v[186:189], v145 offset:2048
	ds_read_b128 v[208:211], v145 offset:3072
	s_add_u32 s62, s62, 0x40000
	s_addc_u32 s63, s63, 0
	s_mov_b32 m0, s54
	v_lshl_add_u64 v[248:249], s[62:63], 0, v[134:135]
	ds_read_b128 v[212:215], v168 offset:32768
	ds_read_b128 v[216:219], v168 offset:33792
	ds_read_b128 v[220:223], v168 offset:34816
	ds_read_b128 v[224:227], v168 offset:35840
	ds_read_b128 v[228:231], v168 offset:36864
	ds_read_b128 v[232:235], v168 offset:37888
	ds_read_b128 v[236:239], v168 offset:38912
	ds_read_b128 v[240:243], v168 offset:39936
	global_load_lds_dwordx4 v[248:249], off
	v_lshl_add_u64 v[248:249], s[62:63], 0, v[130:131]
	s_mov_b32 m0, s55
	s_nop 0
	global_load_lds_dwordx4 v[248:249], off
	s_cmp_eq_u32 s64, -2
	s_cbranch_scc0 .Lrw8_ip2
	s_cmp_gt_u32 s35, 1
	s_cbranch_scc0 .Lrw8_ip2
	s_waitcnt vmcnt(26)
	s_branch .Lrwd_ip2

.Lrwd_ip2:
	s_waitcnt lgkmcnt(0)
	s_barrier
	s_waitcnt lgkmcnt(0)
	v_mfma_f32_16x16x32_bf16 v[124:127], v[146:149], v[212:215], v[124:127]
	v_mfma_f32_16x16x32_bf16 v[120:123], v[154:157], v[212:215], v[120:123]
	v_mfma_f32_16x16x32_bf16 v[116:119], v[146:149], v[220:223], v[116:119]
	v_mfma_f32_16x16x32_bf16 v[112:115], v[154:157], v[220:223], v[112:115]
	v_mfma_f32_16x16x32_bf16 v[100:103], v[146:149], v[228:231], v[100:103]
	v_mfma_f32_16x16x32_bf16 v[96:99], v[154:157], v[228:231], v[96:99]
	v_mfma_f32_16x16x32_bf16 v[84:87], v[146:149], v[236:239], v[84:87]
	v_mfma_f32_16x16x32_bf16 v[80:83], v[154:157], v[236:239], v[80:83]
	v_mfma_f32_16x16x32_bf16 v[124:127], v[150:153], v[216:219], v[124:127]
	v_mfma_f32_16x16x32_bf16 v[120:123], v[170:173], v[216:219], v[120:123]
	v_mfma_f32_16x16x32_bf16 v[116:119], v[150:153], v[224:227], v[116:119]
	v_mfma_f32_16x16x32_bf16 v[112:115], v[170:173], v[224:227], v[112:115]
	v_mfma_f32_16x16x32_bf16 v[100:103], v[150:153], v[232:235], v[100:103]
	v_mfma_f32_16x16x32_bf16 v[96:99], v[170:173], v[232:235], v[96:99]
	v_mfma_f32_16x16x32_bf16 v[84:87], v[150:153], v[240:243], v[84:87]
	v_mfma_f32_16x16x32_bf16 v[80:83], v[170:173], v[240:243], v[80:83]
	v_mfma_f32_16x16x32_bf16 v[108:111], v[178:181], v[212:215], v[108:111]
	v_mfma_f32_16x16x32_bf16 v[104:107], v[186:189], v[212:215], v[104:107]
	v_mfma_f32_16x16x32_bf16 v[92:95], v[178:181], v[220:223], v[92:95]
	v_mfma_f32_16x16x32_bf16 v[88:91], v[186:189], v[220:223], v[88:91]
	v_mfma_f32_16x16x32_bf16 v[76:79], v[178:181], v[228:231], v[76:79]
	v_mfma_f32_16x16x32_bf16 v[72:75], v[186:189], v[228:231], v[72:75]
	v_mfma_f32_16x16x32_bf16 v[68:71], v[178:181], v[236:239], v[68:71]
	v_mfma_f32_16x16x32_bf16 v[64:67], v[186:189], v[236:239], v[64:67]
	v_mfma_f32_16x16x32_bf16 v[108:111], v[182:185], v[216:219], v[108:111]
	v_mfma_f32_16x16x32_bf16 v[104:107], v[208:211], v[216:219], v[104:107]
	v_mfma_f32_16x16x32_bf16 v[92:95], v[182:185], v[224:227], v[92:95]
	v_mfma_f32_16x16x32_bf16 v[88:91], v[208:211], v[224:227], v[88:91]
	v_mfma_f32_16x16x32_bf16 v[76:79], v[182:185], v[232:235], v[76:79]
	v_mfma_f32_16x16x32_bf16 v[72:75], v[208:211], v[232:235], v[72:75]
	v_mfma_f32_16x16x32_bf16 v[68:71], v[182:185], v[240:243], v[68:71]
	v_mfma_f32_16x16x32_bf16 v[64:67], v[208:211], v[240:243], v[64:67]
	s_barrier
	s_add_i32 s37, s37, s52
	v_lshl_add_u64 v[158:159], v[158:159], 0, s[26:27]
	s_mov_b32 m0, s37
	ds_read_b128 v[212:215], v168 offset:49152
	ds_read_b128 v[216:219], v168 offset:50176
	ds_read_b128 v[220:223], v168 offset:51200
	ds_read_b128 v[224:227], v168 offset:52224
	ds_read_b128 v[228:231], v168 offset:53248
	ds_read_b128 v[232:235], v168 offset:54272
	ds_read_b128 v[236:239], v168 offset:55296
	ds_read_b128 v[240:243], v168 offset:56320
	global_load_lds_dwordx4 v[158:159], off
	s_add_i32 m0, s37, 0x2000
	s_add_u32 s44, s44, 0x10080
	v_lshl_add_u64 v[158:159], v[174:175], 0, s[26:27]
	s_addc_u32 s45, s45, 0
	s_add_i32 s37, s39, s52
	global_load_lds_dwordx4 v[158:159], off
	v_lshl_add_u64 v[158:159], s[44:45], 0, v[132:133]
	s_mov_b32 m0, s37
	s_nop 0
	global_load_lds_dwordx4 v[158:159], off
	v_lshl_add_u64 v[158:159], s[44:45], 0, v[128:129]
	s_add_i32 m0, s37, 0x2000
	s_nop 0
	global_load_lds_dwordx4 v[158:159], off
	v_lshl_add_u64 v[158:159], v[244:245], 0, s[26:27]
	s_mov_b32 m0, s34
	s_nop 0
	global_load_lds_dwordx4 v[158:159], off
	v_lshl_add_u64 v[158:159], v[246:247], 0, s[26:27]
	s_mov_b32 m0, s53
	s_nop 0
	global_load_lds_dwordx4 v[158:159], off
	s_waitcnt vmcnt(8)
	s_waitcnt lgkmcnt(0)
	s_barrier
	s_waitcnt lgkmcnt(0)
	v_mfma_f32_16x16x32_bf16 v[60:63], v[146:149], v[212:215], v[60:63]
	v_mfma_f32_16x16x32_bf16 v[56:59], v[154:157], v[212:215], v[56:59]
	v_mfma_f32_16x16x32_bf16 v[52:55], v[146:149], v[220:223], v[52:55]
	v_mfma_f32_16x16x32_bf16 v[48:51], v[154:157], v[220:223], v[48:51]
	v_mfma_f32_16x16x32_bf16 v[36:39], v[146:149], v[228:231], v[36:39]
	v_mfma_f32_16x16x32_bf16 v[32:35], v[154:157], v[228:231], v[32:35]
	v_mfma_f32_16x16x32_bf16 v[20:23], v[146:149], v[236:239], v[20:23]
	v_mfma_f32_16x16x32_bf16 v[16:19], v[154:157], v[236:239], v[16:19]
	v_mfma_f32_16x16x32_bf16 v[60:63], v[150:153], v[216:219], v[60:63]
	v_mfma_f32_16x16x32_bf16 v[56:59], v[170:173], v[216:219], v[56:59]
	v_mfma_f32_16x16x32_bf16 v[52:55], v[150:153], v[224:227], v[52:55]
	v_mfma_f32_16x16x32_bf16 v[48:51], v[170:173], v[224:227], v[48:51]
	v_mfma_f32_16x16x32_bf16 v[36:39], v[150:153], v[232:235], v[36:39]
	v_mfma_f32_16x16x32_bf16 v[32:35], v[170:173], v[232:235], v[32:35]
	v_mfma_f32_16x16x32_bf16 v[20:23], v[150:153], v[240:243], v[20:23]
	v_mfma_f32_16x16x32_bf16 v[16:19], v[170:173], v[240:243], v[16:19]
	v_mfma_f32_16x16x32_bf16 v[44:47], v[178:181], v[212:215], v[44:47]
	v_mfma_f32_16x16x32_bf16 v[40:43], v[186:189], v[212:215], v[40:43]
	v_mfma_f32_16x16x32_bf16 v[28:31], v[178:181], v[220:223], v[28:31]
	v_mfma_f32_16x16x32_bf16 v[24:27], v[186:189], v[220:223], v[24:27]
	v_mfma_f32_16x16x32_bf16 v[12:15], v[178:181], v[228:231], v[12:15]
	v_mfma_f32_16x16x32_bf16 v[8:11], v[186:189], v[228:231], v[8:11]
	v_mfma_f32_16x16x32_bf16 v[4:7], v[178:181], v[236:239], v[4:7]
	v_mfma_f32_16x16x32_bf16 v[0:3], v[186:189], v[236:239], v[0:3]
	v_mfma_f32_16x16x32_bf16 v[44:47], v[182:185], v[216:219], v[44:47]
	v_mfma_f32_16x16x32_bf16 v[40:43], v[208:211], v[216:219], v[40:43]
	v_mfma_f32_16x16x32_bf16 v[28:31], v[182:185], v[224:227], v[28:31]
	v_mfma_f32_16x16x32_bf16 v[24:27], v[208:211], v[224:227], v[24:27]
	v_mfma_f32_16x16x32_bf16 v[12:15], v[182:185], v[232:235], v[12:15]
	v_mfma_f32_16x16x32_bf16 v[8:11], v[208:211], v[232:235], v[8:11]
	v_mfma_f32_16x16x32_bf16 v[4:7], v[182:185], v[240:243], v[4:7]
	v_mfma_f32_16x16x32_bf16 v[0:3], v[208:211], v[240:243], v[0:3]
	s_barrier
	s_add_i32 s64, s64, 2
	s_add_u32 s42, s42, 0x100
	s_addc_u32 s43, s43, 0
	s_add_u32 s22, s22, 0x100
	s_addc_u32 s30, s30, 0
	s_cmp_gt_u32 s64, 13
	s_cbranch_scc0 .LBB0_645
	v_readlane_b32 s0, v252, 26
	v_readlane_b32 s1, v252, 27
	s_and_b64 vcc, exec, s[0:1]
	v_readlane_b32 s68, v252, 11
	v_readlane_b32 s69, v252, 12
	s_cbranch_vccz .LBB0_648
	s_barrier

.Lrwd_ip20:
	s_waitcnt lgkmcnt(0)
	s_barrier
	s_waitcnt lgkmcnt(0)
	v_mfma_f32_16x16x32_bf16 v[124:127], v[146:149], v[212:215], v[124:127]
	v_mfma_f32_16x16x32_bf16 v[120:123], v[154:157], v[212:215], v[120:123]
	v_mfma_f32_16x16x32_bf16 v[116:119], v[146:149], v[220:223], v[116:119]
	v_mfma_f32_16x16x32_bf16 v[112:115], v[154:157], v[220:223], v[112:115]
	v_mfma_f32_16x16x32_bf16 v[100:103], v[146:149], v[228:231], v[100:103]
	v_mfma_f32_16x16x32_bf16 v[96:99], v[154:157], v[228:231], v[96:99]
	v_mfma_f32_16x16x32_bf16 v[84:87], v[146:149], v[236:239], v[84:87]
	v_mfma_f32_16x16x32_bf16 v[80:83], v[154:157], v[236:239], v[80:83]
	v_mfma_f32_16x16x32_bf16 v[124:127], v[150:153], v[216:219], v[124:127]
	v_mfma_f32_16x16x32_bf16 v[120:123], v[170:173], v[216:219], v[120:123]
	v_mfma_f32_16x16x32_bf16 v[116:119], v[150:153], v[224:227], v[116:119]
	v_mfma_f32_16x16x32_bf16 v[112:115], v[170:173], v[224:227], v[112:115]
	v_mfma_f32_16x16x32_bf16 v[100:103], v[150:153], v[232:235], v[100:103]
	v_mfma_f32_16x16x32_bf16 v[96:99], v[170:173], v[232:235], v[96:99]
	v_mfma_f32_16x16x32_bf16 v[84:87], v[150:153], v[240:243], v[84:87]
	v_mfma_f32_16x16x32_bf16 v[80:83], v[170:173], v[240:243], v[80:83]
	v_mfma_f32_16x16x32_bf16 v[108:111], v[178:181], v[212:215], v[108:111]
	v_mfma_f32_16x16x32_bf16 v[104:107], v[186:189], v[212:215], v[104:107]
	v_mfma_f32_16x16x32_bf16 v[92:95], v[178:181], v[220:223], v[92:95]
	v_mfma_f32_16x16x32_bf16 v[88:91], v[186:189], v[220:223], v[88:91]
	v_mfma_f32_16x16x32_bf16 v[76:79], v[178:181], v[228:231], v[76:79]
	v_mfma_f32_16x16x32_bf16 v[72:75], v[186:189], v[228:231], v[72:75]
	v_mfma_f32_16x16x32_bf16 v[68:71], v[178:181], v[236:239], v[68:71]
	v_mfma_f32_16x16x32_bf16 v[64:67], v[186:189], v[236:239], v[64:67]
	v_mfma_f32_16x16x32_bf16 v[108:111], v[182:185], v[216:219], v[108:111]
	v_mfma_f32_16x16x32_bf16 v[104:107], v[208:211], v[216:219], v[104:107]
	v_mfma_f32_16x16x32_bf16 v[92:95], v[182:185], v[224:227], v[92:95]
	v_mfma_f32_16x16x32_bf16 v[88:91], v[208:211], v[224:227], v[88:91]
	v_mfma_f32_16x16x32_bf16 v[76:79], v[182:185], v[232:235], v[76:79]
	v_mfma_f32_16x16x32_bf16 v[72:75], v[208:211], v[232:235], v[72:75]
	v_mfma_f32_16x16x32_bf16 v[68:71], v[182:185], v[240:243], v[68:71]
	v_mfma_f32_16x16x32_bf16 v[64:67], v[208:211], v[240:243], v[64:67]
	s_barrier
	s_add_i32 s39, s65, s52
	v_lshl_add_u64 v[158:159], s[44:45], 0, v[132:133]
	s_mov_b32 m0, s39
	ds_read_b128 v[212:215], v168 offset:16384
	ds_read_b128 v[216:219], v168 offset:17408
	ds_read_b128 v[220:223], v168 offset:18432
	ds_read_b128 v[224:227], v168 offset:19456
	ds_read_b128 v[228:231], v168 offset:20480
	ds_read_b128 v[232:235], v168 offset:21504
	ds_read_b128 v[236:239], v168 offset:22528
	ds_read_b128 v[240:243], v168 offset:23552
	global_load_lds_dwordx4 v[158:159], off
	s_add_i32 m0, s39, 0x2000
	s_add_u32 s66, s44, 0x10000
	v_lshl_add_u64 v[174:175], s[44:45], 0, v[128:129]
	s_addc_u32 s67, s45, 0
	s_add_i32 s37, s37, s52
	global_load_lds_dwordx4 v[174:175], off
	v_lshl_add_u64 v[244:245], s[66:67], 0, v[132:133]
	s_mov_b32 m0, s37
	v_lshl_add_u64 v[246:247], s[62:63], 0, v[130:131]
	global_load_lds_dwordx4 v[244:245], off
	v_lshl_add_u64 v[244:245], s[66:67], 0, v[128:129]
	s_add_i32 m0, s37, 0x2000
	s_nop 0
	global_load_lds_dwordx4 v[244:245], off
	v_lshl_add_u64 v[244:245], s[62:63], 0, v[134:135]
	s_mov_b32 m0, s56
	s_nop 0
	global_load_lds_dwordx4 v[244:245], off
	s_mov_b32 m0, s57
	s_nop 0
	global_load_lds_dwordx4 v[246:247], off
	s_cmp_eq_u32 s64, -2
	s_cbranch_scc0 .Lrw8_ip21
	s_cmp_gt_u32 s34, 1
	s_cbranch_scc0 .Lrw8_ip21
	s_waitcnt vmcnt(24)
	s_branch .Lrwd_ip21

.Lrwd_ip21:
	s_waitcnt lgkmcnt(0)
	s_barrier
	s_waitcnt lgkmcnt(0)
	v_mfma_f32_16x16x32_bf16 v[60:63], v[146:149], v[212:215], v[60:63]
	v_mfma_f32_16x16x32_bf16 v[56:59], v[154:157], v[212:215], v[56:59]
	v_mfma_f32_16x16x32_bf16 v[52:55], v[146:149], v[220:223], v[52:55]
	v_mfma_f32_16x16x32_bf16 v[48:51], v[154:157], v[220:223], v[48:51]
	v_mfma_f32_16x16x32_bf16 v[36:39], v[146:149], v[228:231], v[36:39]
	v_mfma_f32_16x16x32_bf16 v[32:35], v[154:157], v[228:231], v[32:35]
	v_mfma_f32_16x16x32_bf16 v[20:23], v[146:149], v[236:239], v[20:23]
	v_mfma_f32_16x16x32_bf16 v[16:19], v[154:157], v[236:239], v[16:19]
	v_mfma_f32_16x16x32_bf16 v[60:63], v[150:153], v[216:219], v[60:63]
	v_mfma_f32_16x16x32_bf16 v[56:59], v[170:173], v[216:219], v[56:59]
	v_mfma_f32_16x16x32_bf16 v[52:55], v[150:153], v[224:227], v[52:55]
	v_mfma_f32_16x16x32_bf16 v[48:51], v[170:173], v[224:227], v[48:51]
	v_mfma_f32_16x16x32_bf16 v[36:39], v[150:153], v[232:235], v[36:39]
	v_mfma_f32_16x16x32_bf16 v[32:35], v[170:173], v[232:235], v[32:35]
	v_mfma_f32_16x16x32_bf16 v[20:23], v[150:153], v[240:243], v[20:23]
	v_mfma_f32_16x16x32_bf16 v[16:19], v[170:173], v[240:243], v[16:19]
	v_mfma_f32_16x16x32_bf16 v[44:47], v[178:181], v[212:215], v[44:47]
	v_mfma_f32_16x16x32_bf16 v[40:43], v[186:189], v[212:215], v[40:43]
	v_mfma_f32_16x16x32_bf16 v[28:31], v[178:181], v[220:223], v[28:31]
	v_mfma_f32_16x16x32_bf16 v[24:27], v[186:189], v[220:223], v[24:27]
	v_mfma_f32_16x16x32_bf16 v[12:15], v[178:181], v[228:231], v[12:15]
	v_mfma_f32_16x16x32_bf16 v[8:11], v[186:189], v[228:231], v[8:11]
	v_mfma_f32_16x16x32_bf16 v[4:7], v[178:181], v[236:239], v[4:7]
	v_mfma_f32_16x16x32_bf16 v[0:3], v[186:189], v[236:239], v[0:3]
	v_mfma_f32_16x16x32_bf16 v[44:47], v[182:185], v[216:219], v[44:47]
	v_mfma_f32_16x16x32_bf16 v[40:43], v[208:211], v[216:219], v[40:43]
	v_mfma_f32_16x16x32_bf16 v[28:31], v[182:185], v[224:227], v[28:31]
	v_mfma_f32_16x16x32_bf16 v[24:27], v[208:211], v[224:227], v[24:27]
	v_mfma_f32_16x16x32_bf16 v[12:15], v[182:185], v[232:235], v[12:15]
	v_mfma_f32_16x16x32_bf16 v[8:11], v[208:211], v[232:235], v[8:11]
	v_mfma_f32_16x16x32_bf16 v[4:7], v[182:185], v[240:243], v[4:7]
	v_mfma_f32_16x16x32_bf16 v[0:3], v[208:211], v[240:243], v[0:3]
	s_barrier
	s_add_i32 s37, 0, 0x18000
	v_add_u32_e32 v145, s37, v162
	s_add_i32 s39, 0, 0x1c000
	ds_read_b128 v[146:149], v145
	ds_read_b128 v[150:153], v145 offset:1024
	ds_read_b128 v[154:157], v145 offset:2048
	ds_read_b128 v[170:173], v145 offset:3072
	v_add_u32_e32 v145, s39, v162
	ds_read_b128 v[178:181], v145
	ds_read_b128 v[182:185], v145 offset:1024
	ds_read_b128 v[186:189], v145 offset:2048
	ds_read_b128 v[208:211], v145 offset:3072
	s_add_u32 s62, s62, 0x40000
	s_addc_u32 s63, s63, 0
	s_mov_b32 m0, s54
	v_lshl_add_u64 v[248:249], s[62:63], 0, v[134:135]
	ds_read_b128 v[212:215], v168 offset:32768
	ds_read_b128 v[216:219], v168 offset:33792
	ds_read_b128 v[220:223], v168 offset:34816
	ds_read_b128 v[224:227], v168 offset:35840
	ds_read_b128 v[228:231], v168 offset:36864
	ds_read_b128 v[232:235], v168 offset:37888
	ds_read_b128 v[236:239], v168 offset:38912
	ds_read_b128 v[240:243], v168 offset:39936
	global_load_lds_dwordx4 v[248:249], off
	v_lshl_add_u64 v[248:249], s[62:63], 0, v[130:131]
	s_mov_b32 m0, s55
	s_nop 0
	global_load_lds_dwordx4 v[248:249], off
	s_cmp_eq_u32 s64, -2
	s_cbranch_scc0 .Lrw8_ip22
	s_cmp_gt_u32 s34, 1
	s_cbranch_scc0 .Lrw8_ip22
	s_waitcnt vmcnt(26)
	s_branch .Lrwd_ip22

.Lrwd_ip22:
	s_waitcnt lgkmcnt(0)
	s_barrier
	s_waitcnt lgkmcnt(0)
	v_mfma_f32_16x16x32_bf16 v[124:127], v[146:149], v[212:215], v[124:127]
	v_mfma_f32_16x16x32_bf16 v[120:123], v[154:157], v[212:215], v[120:123]
	v_mfma_f32_16x16x32_bf16 v[116:119], v[146:149], v[220:223], v[116:119]
	v_mfma_f32_16x16x32_bf16 v[112:115], v[154:157], v[220:223], v[112:115]
	v_mfma_f32_16x16x32_bf16 v[100:103], v[146:149], v[228:231], v[100:103]
	v_mfma_f32_16x16x32_bf16 v[96:99], v[154:157], v[228:231], v[96:99]
	v_mfma_f32_16x16x32_bf16 v[84:87], v[146:149], v[236:239], v[84:87]
	v_mfma_f32_16x16x32_bf16 v[80:83], v[154:157], v[236:239], v[80:83]
	v_mfma_f32_16x16x32_bf16 v[124:127], v[150:153], v[216:219], v[124:127]
	v_mfma_f32_16x16x32_bf16 v[120:123], v[170:173], v[216:219], v[120:123]
	v_mfma_f32_16x16x32_bf16 v[116:119], v[150:153], v[224:227], v[116:119]
	v_mfma_f32_16x16x32_bf16 v[112:115], v[170:173], v[224:227], v[112:115]
	v_mfma_f32_16x16x32_bf16 v[100:103], v[150:153], v[232:235], v[100:103]
	v_mfma_f32_16x16x32_bf16 v[96:99], v[170:173], v[232:235], v[96:99]
	v_mfma_f32_16x16x32_bf16 v[84:87], v[150:153], v[240:243], v[84:87]
	v_mfma_f32_16x16x32_bf16 v[80:83], v[170:173], v[240:243], v[80:83]
	v_mfma_f32_16x16x32_bf16 v[108:111], v[178:181], v[212:215], v[108:111]
	v_mfma_f32_16x16x32_bf16 v[104:107], v[186:189], v[212:215], v[104:107]
	v_mfma_f32_16x16x32_bf16 v[92:95], v[178:181], v[220:223], v[92:95]
	v_mfma_f32_16x16x32_bf16 v[88:91], v[186:189], v[220:223], v[88:91]
	v_mfma_f32_16x16x32_bf16 v[76:79], v[178:181], v[228:231], v[76:79]
	v_mfma_f32_16x16x32_bf16 v[72:75], v[186:189], v[228:231], v[72:75]
	v_mfma_f32_16x16x32_bf16 v[68:71], v[178:181], v[236:239], v[68:71]
	v_mfma_f32_16x16x32_bf16 v[64:67], v[186:189], v[236:239], v[64:67]
	v_mfma_f32_16x16x32_bf16 v[108:111], v[182:185], v[216:219], v[108:111]
	v_mfma_f32_16x16x32_bf16 v[104:107], v[208:211], v[216:219], v[104:107]
	v_mfma_f32_16x16x32_bf16 v[92:95], v[182:185], v[224:227], v[92:95]
	v_mfma_f32_16x16x32_bf16 v[88:91], v[208:211], v[224:227], v[88:91]
	v_mfma_f32_16x16x32_bf16 v[76:79], v[182:185], v[232:235], v[76:79]
	v_mfma_f32_16x16x32_bf16 v[72:75], v[208:211], v[232:235], v[72:75]
	v_mfma_f32_16x16x32_bf16 v[68:71], v[182:185], v[240:243], v[68:71]
	v_mfma_f32_16x16x32_bf16 v[64:67], v[208:211], v[240:243], v[64:67]
	s_barrier
	s_add_i32 s37, s37, s52
	v_lshl_add_u64 v[158:159], v[158:159], 0, s[26:27]
	s_mov_b32 m0, s37
	ds_read_b128 v[212:215], v168 offset:49152
	ds_read_b128 v[216:219], v168 offset:50176
	ds_read_b128 v[220:223], v168 offset:51200
	ds_read_b128 v[224:227], v168 offset:52224
	ds_read_b128 v[228:231], v168 offset:53248
	ds_read_b128 v[232:235], v168 offset:54272
	ds_read_b128 v[236:239], v168 offset:55296
	ds_read_b128 v[240:243], v168 offset:56320
	global_load_lds_dwordx4 v[158:159], off
	s_add_i32 m0, s37, 0x2000
	s_add_u32 s44, s44, 0x10080
	v_lshl_add_u64 v[158:159], v[174:175], 0, s[26:27]
	s_addc_u32 s45, s45, 0
	s_add_i32 s37, s39, s52
	global_load_lds_dwordx4 v[158:159], off
	v_lshl_add_u64 v[158:159], s[44:45], 0, v[132:133]
	s_mov_b32 m0, s37
	s_nop 0
	global_load_lds_dwordx4 v[158:159], off
	v_lshl_add_u64 v[158:159], s[44:45], 0, v[128:129]
	s_add_i32 m0, s37, 0x2000
	s_nop 0
	global_load_lds_dwordx4 v[158:159], off
	v_lshl_add_u64 v[158:159], v[244:245], 0, s[26:27]
	s_mov_b32 m0, s35
	s_nop 0
	global_load_lds_dwordx4 v[158:159], off
	v_lshl_add_u64 v[158:159], v[246:247], 0, s[26:27]
	s_mov_b32 m0, s53
	s_nop 0
	global_load_lds_dwordx4 v[158:159], off
	s_waitcnt vmcnt(8)
	s_waitcnt lgkmcnt(0)
	s_barrier
	s_waitcnt lgkmcnt(0)
	v_mfma_f32_16x16x32_bf16 v[60:63], v[146:149], v[212:215], v[60:63]
	v_mfma_f32_16x16x32_bf16 v[56:59], v[154:157], v[212:215], v[56:59]
	v_mfma_f32_16x16x32_bf16 v[52:55], v[146:149], v[220:223], v[52:55]
	v_mfma_f32_16x16x32_bf16 v[48:51], v[154:157], v[220:223], v[48:51]
	v_mfma_f32_16x16x32_bf16 v[36:39], v[146:149], v[228:231], v[36:39]
	v_mfma_f32_16x16x32_bf16 v[32:35], v[154:157], v[228:231], v[32:35]
	v_mfma_f32_16x16x32_bf16 v[20:23], v[146:149], v[236:239], v[20:23]
	v_mfma_f32_16x16x32_bf16 v[16:19], v[154:157], v[236:239], v[16:19]
	v_mfma_f32_16x16x32_bf16 v[60:63], v[150:153], v[216:219], v[60:63]
	v_mfma_f32_16x16x32_bf16 v[56:59], v[170:173], v[216:219], v[56:59]
	v_mfma_f32_16x16x32_bf16 v[52:55], v[150:153], v[224:227], v[52:55]
	v_mfma_f32_16x16x32_bf16 v[48:51], v[170:173], v[224:227], v[48:51]
	v_mfma_f32_16x16x32_bf16 v[36:39], v[150:153], v[232:235], v[36:39]
	v_mfma_f32_16x16x32_bf16 v[32:35], v[170:173], v[232:235], v[32:35]
	v_mfma_f32_16x16x32_bf16 v[20:23], v[150:153], v[240:243], v[20:23]
	v_mfma_f32_16x16x32_bf16 v[16:19], v[170:173], v[240:243], v[16:19]
	v_mfma_f32_16x16x32_bf16 v[44:47], v[178:181], v[212:215], v[44:47]
	v_mfma_f32_16x16x32_bf16 v[40:43], v[186:189], v[212:215], v[40:43]
	v_mfma_f32_16x16x32_bf16 v[28:31], v[178:181], v[220:223], v[28:31]
	v_mfma_f32_16x16x32_bf16 v[24:27], v[186:189], v[220:223], v[24:27]
	v_mfma_f32_16x16x32_bf16 v[12:15], v[178:181], v[228:231], v[12:15]
	v_mfma_f32_16x16x32_bf16 v[8:11], v[186:189], v[228:231], v[8:11]
	v_mfma_f32_16x16x32_bf16 v[4:7], v[178:181], v[236:239], v[4:7]
	v_mfma_f32_16x16x32_bf16 v[0:3], v[186:189], v[236:239], v[0:3]
	v_mfma_f32_16x16x32_bf16 v[44:47], v[182:185], v[216:219], v[44:47]
	v_mfma_f32_16x16x32_bf16 v[40:43], v[208:211], v[216:219], v[40:43]
	v_mfma_f32_16x16x32_bf16 v[28:31], v[182:185], v[224:227], v[28:31]
	v_mfma_f32_16x16x32_bf16 v[24:27], v[208:211], v[224:227], v[24:27]
	v_mfma_f32_16x16x32_bf16 v[12:15], v[182:185], v[232:235], v[12:15]
	v_mfma_f32_16x16x32_bf16 v[8:11], v[208:211], v[232:235], v[8:11]
	v_mfma_f32_16x16x32_bf16 v[4:7], v[182:185], v[240:243], v[4:7]
	v_mfma_f32_16x16x32_bf16 v[0:3], v[208:211], v[240:243], v[0:3]
	s_barrier
	s_add_i32 s64, s64, 2
	s_add_u32 s42, s42, 0x100
	s_addc_u32 s43, s43, 0
	s_add_u32 s22, s22, 0x100
	s_addc_u32 s30, s30, 0
	s_cmp_gt_u32 s64, 13
	s_cbranch_scc0 .LBB0_1180
	v_readlane_b32 s0, v252, 26
	v_readlane_b32 s1, v252, 27
	s_and_b64 vcc, exec, s[0:1]
	v_readlane_b32 s68, v252, 11
	v_readlane_b32 s69, v252, 12
	s_cbranch_vccz .LBB0_1183
	s_barrier
